# v035 + s_sleep 1 removed from the grid-barrier poll loops (tighter polling)
# speedup vs baseline: 1.0031x; 1.0031x over previous
.LBB0_247:
	global_load_dword v17, v18, s[78:79] offset:1024 sc1
	global_load_dword v2, v18, s[78:79] offset:1280 sc1
	global_load_dword v3, v18, s[78:79] offset:1536 sc1
	global_load_dword v4, v18, s[78:79] offset:1792 sc1
	global_load_dword v5, v18, s[78:79] offset:2048 sc1
	global_load_dword v6, v18, s[78:79] offset:2304 sc1
	global_load_dword v7, v18, s[78:79] offset:2560 sc1
	global_load_dword v8, v18, s[78:79] offset:2816 sc1
	global_load_dword v9, v18, s[78:79] offset:3072 sc1
	global_load_dword v10, v18, s[78:79] offset:3328 sc1
	global_load_dword v11, v18, s[78:79] offset:3584 sc1
	global_load_dword v12, v18, s[78:79] offset:3840 sc1
	global_load_dword v13, v18, s[4:5] sc1
	global_load_dword v14, v18, s[6:7] sc1
	global_load_dword v15, v18, s[10:11] sc1
	global_load_dword v16, v18, s[12:13] sc1
	s_mov_b64 s[16:17], -1
	s_mov_b64 s[20:21], -1
	s_waitcnt vmcnt(14)
	v_add_u32_e32 v19, v2, v17
	s_waitcnt vmcnt(13)
	v_add_u32_e32 v19, v19, v3
	s_waitcnt vmcnt(12)
	v_add_u32_e32 v19, v19, v4
	s_waitcnt vmcnt(11)
	v_add_u32_e32 v19, v19, v5
	s_waitcnt vmcnt(10)
	v_add_u32_e32 v19, v19, v6
	s_waitcnt vmcnt(9)
	v_add_u32_e32 v19, v19, v7
	s_waitcnt vmcnt(8)
	v_add_u32_e32 v19, v19, v8
	s_waitcnt vmcnt(7)
	v_add_u32_e32 v19, v19, v9
	s_waitcnt vmcnt(6)
	v_add_u32_e32 v19, v19, v10
	s_waitcnt vmcnt(5)
	v_add_u32_e32 v19, v19, v11
	s_waitcnt vmcnt(4)
	v_add_u32_e32 v19, v19, v12
	s_waitcnt vmcnt(3)
	v_add_u32_e32 v19, v19, v13
	s_waitcnt vmcnt(2)
	v_add_u32_e32 v19, v19, v14
	s_waitcnt vmcnt(1)
	v_add_u32_e32 v19, v19, v15
	s_waitcnt vmcnt(0)
	v_add_u32_e32 v19, v19, v16
	v_cmp_eq_u32_e32 vcc, s26, v19
	s_cbranch_vccnz .LBB0_246
	s_and_b32 s16, s27, 0xff
	s_cmp_eq_u32 s16, 0
	s_mov_b64 s[16:17], -1
	s_mov_b64 s[24:25], -1
	s_nop 0
	s_cbranch_scc1 .LBB0_251
	s_and_b64 vcc, exec, s[24:25]
	s_cbranch_vccz .LBB0_246

.LBB0_263:
	s_and_b32 s26, s30, 0xff
	s_mov_b64 s[24:25], -1
	s_cmp_lg_u32 s26, 0
	s_mov_b64 s[28:29], -1
	s_nop 0
	s_cbranch_scc0 .LBB0_266
	s_and_b64 vcc, exec, s[28:29]
	s_cbranch_vccz .LBB0_262

.LBB0_280:
	s_and_b32 s26, s34, 0xff
	s_cmp_lg_u32 s26, 0
	s_mov_b64 s[28:29], -1
	s_nop 0
	s_cbranch_scc0 .LBB0_283
	s_mov_b64 s[30:31], -1
	s_and_b64 vcc, exec, s[28:29]
	s_cbranch_vccz .LBB0_279

.LBB0_342:
	global_load_dword v17, v18, s[78:79] offset:1024 sc1
	global_load_dword v2, v18, s[78:79] offset:1280 sc1
	global_load_dword v3, v18, s[78:79] offset:1536 sc1
	global_load_dword v4, v18, s[78:79] offset:1792 sc1
	global_load_dword v5, v18, s[78:79] offset:2048 sc1
	global_load_dword v6, v18, s[78:79] offset:2304 sc1
	global_load_dword v7, v18, s[78:79] offset:2560 sc1
	global_load_dword v8, v18, s[78:79] offset:2816 sc1
	global_load_dword v9, v18, s[78:79] offset:3072 sc1
	global_load_dword v10, v18, s[78:79] offset:3328 sc1
	global_load_dword v11, v18, s[78:79] offset:3584 sc1
	global_load_dword v12, v18, s[78:79] offset:3840 sc1
	global_load_dword v13, v18, s[4:5] sc1
	global_load_dword v14, v18, s[6:7] sc1
	global_load_dword v15, v18, s[8:9] sc1
	global_load_dword v16, v18, s[10:11] sc1
	s_mov_b64 s[12:13], -1
	s_mov_b64 s[16:17], -1
	s_waitcnt vmcnt(14)
	v_add_u32_e32 v19, v2, v17
	s_waitcnt vmcnt(13)
	v_add_u32_e32 v19, v19, v3
	s_waitcnt vmcnt(12)
	v_add_u32_e32 v19, v19, v4
	s_waitcnt vmcnt(11)
	v_add_u32_e32 v19, v19, v5
	s_waitcnt vmcnt(10)
	v_add_u32_e32 v19, v19, v6
	s_waitcnt vmcnt(9)
	v_add_u32_e32 v19, v19, v7
	s_waitcnt vmcnt(8)
	v_add_u32_e32 v19, v19, v8
	s_waitcnt vmcnt(7)
	v_add_u32_e32 v19, v19, v9
	s_waitcnt vmcnt(6)
	v_add_u32_e32 v19, v19, v10
	s_waitcnt vmcnt(5)
	v_add_u32_e32 v19, v19, v11
	s_waitcnt vmcnt(4)
	v_add_u32_e32 v19, v19, v12
	s_waitcnt vmcnt(3)
	v_add_u32_e32 v19, v19, v13
	s_waitcnt vmcnt(2)
	v_add_u32_e32 v19, v19, v14
	s_waitcnt vmcnt(1)
	v_add_u32_e32 v19, v19, v15
	s_waitcnt vmcnt(0)
	v_add_u32_e32 v19, v19, v16
	v_cmp_eq_u32_e32 vcc, s22, v19
	s_cbranch_vccnz .LBB0_341
	s_and_b32 s12, s23, 0xff
	s_cmp_eq_u32 s12, 0
	s_mov_b64 s[12:13], -1
	s_mov_b64 s[20:21], -1
	s_nop 0
	s_cbranch_scc1 .LBB0_346
	s_and_b64 vcc, exec, s[20:21]
	s_cbranch_vccz .LBB0_341

.LBB0_358:
	s_and_b32 s22, s26, 0xff
	s_mov_b64 s[20:21], -1
	s_cmp_lg_u32 s22, 0
	s_mov_b64 s[24:25], -1
	s_nop 0
	s_cbranch_scc0 .LBB0_361
	s_and_b64 vcc, exec, s[24:25]
	s_cbranch_vccz .LBB0_357

.LBB0_375:
	s_and_b32 s22, s28, 0xff
	s_cmp_lg_u32 s22, 0
	s_mov_b64 s[24:25], -1
	s_nop 0
	s_cbranch_scc0 .LBB0_378
	s_mov_b64 s[26:27], -1
	s_and_b64 vcc, exec, s[24:25]
	s_cbranch_vccz .LBB0_374

.LBB0_1399:
	global_load_dword v17, v18, s[78:79] offset:1024 sc1
	global_load_dword v2, v18, s[78:79] offset:1280 sc1
	global_load_dword v3, v18, s[78:79] offset:1536 sc1
	global_load_dword v4, v18, s[78:79] offset:1792 sc1
	global_load_dword v5, v18, s[78:79] offset:2048 sc1
	global_load_dword v6, v18, s[78:79] offset:2304 sc1
	global_load_dword v7, v18, s[78:79] offset:2560 sc1
	global_load_dword v8, v18, s[78:79] offset:2816 sc1
	global_load_dword v9, v18, s[78:79] offset:3072 sc1
	global_load_dword v10, v18, s[78:79] offset:3328 sc1
	global_load_dword v11, v18, s[78:79] offset:3584 sc1
	global_load_dword v12, v18, s[78:79] offset:3840 sc1
	global_load_dword v13, v18, s[4:5] sc1
	global_load_dword v14, v18, s[6:7] sc1
	global_load_dword v15, v18, s[8:9] sc1
	global_load_dword v16, v18, s[10:11] sc1
	s_mov_b64 s[12:13], -1
	s_mov_b64 s[14:15], -1
	s_waitcnt vmcnt(14)
	v_add_u32_e32 v19, v2, v17
	s_waitcnt vmcnt(13)
	v_add_u32_e32 v19, v19, v3
	s_waitcnt vmcnt(12)
	v_add_u32_e32 v19, v19, v4
	s_waitcnt vmcnt(11)
	v_add_u32_e32 v19, v19, v5
	s_waitcnt vmcnt(10)
	v_add_u32_e32 v19, v19, v6
	s_waitcnt vmcnt(9)
	v_add_u32_e32 v19, v19, v7
	s_waitcnt vmcnt(8)
	v_add_u32_e32 v19, v19, v8
	s_waitcnt vmcnt(7)
	v_add_u32_e32 v19, v19, v9
	s_waitcnt vmcnt(6)
	v_add_u32_e32 v19, v19, v10
	s_waitcnt vmcnt(5)
	v_add_u32_e32 v19, v19, v11
	s_waitcnt vmcnt(4)
	v_add_u32_e32 v19, v19, v12
	s_waitcnt vmcnt(3)
	v_add_u32_e32 v19, v19, v13
	s_waitcnt vmcnt(2)
	v_add_u32_e32 v19, v19, v14
	s_waitcnt vmcnt(1)
	v_add_u32_e32 v19, v19, v15
	s_waitcnt vmcnt(0)
	v_add_u32_e32 v19, v19, v16
	v_cmp_eq_u32_e32 vcc, s18, v19
	s_cbranch_vccnz .LBB0_1398
	s_and_b32 s12, s19, 0xff
	s_cmp_eq_u32 s12, 0
	s_mov_b64 s[12:13], -1
	s_mov_b64 s[16:17], -1
	s_nop 0
	s_cbranch_scc1 .LBB0_1403
	s_and_b64 vcc, exec, s[16:17]
	s_cbranch_vccz .LBB0_1398

.LBB0_1415:
	s_and_b32 s18, s22, 0xff
	s_mov_b64 s[16:17], -1
	s_cmp_lg_u32 s18, 0
	s_mov_b64 s[20:21], -1
	s_nop 0
	s_cbranch_scc0 .LBB0_1418
	s_and_b64 vcc, exec, s[20:21]
	s_cbranch_vccz .LBB0_1414

.LBB0_1432:
	s_and_b32 s18, s24, 0xff
	s_cmp_lg_u32 s18, 0
	s_mov_b64 s[20:21], -1
	s_nop 0
	s_cbranch_scc0 .LBB0_1435
	s_mov_b64 s[22:23], -1
	s_and_b64 vcc, exec, s[20:21]
	s_cbranch_vccz .LBB0_1431

.LBB0_3949:
	global_load_dword v15, v16, s[78:79] offset:1024 sc1
	global_load_dword v0, v16, s[78:79] offset:1280 sc1
	global_load_dword v1, v16, s[78:79] offset:1536 sc1
	global_load_dword v2, v16, s[78:79] offset:1792 sc1
	global_load_dword v3, v16, s[78:79] offset:2048 sc1
	global_load_dword v4, v16, s[78:79] offset:2304 sc1
	global_load_dword v5, v16, s[78:79] offset:2560 sc1
	global_load_dword v6, v16, s[78:79] offset:2816 sc1
	global_load_dword v7, v16, s[78:79] offset:3072 sc1
	global_load_dword v8, v16, s[78:79] offset:3328 sc1
	global_load_dword v9, v16, s[78:79] offset:3584 sc1
	global_load_dword v10, v16, s[78:79] offset:3840 sc1
	global_load_dword v11, v16, s[2:3] sc1
	global_load_dword v12, v16, s[4:5] sc1
	global_load_dword v13, v16, s[6:7] sc1
	global_load_dword v14, v16, s[8:9] sc1
	s_mov_b64 s[10:11], -1
	s_mov_b64 s[12:13], -1
	s_waitcnt vmcnt(14)
	v_add_u32_e32 v17, v0, v15
	s_waitcnt vmcnt(13)
	v_add_u32_e32 v17, v17, v1
	s_waitcnt vmcnt(12)
	v_add_u32_e32 v17, v17, v2
	s_waitcnt vmcnt(11)
	v_add_u32_e32 v17, v17, v3
	s_waitcnt vmcnt(10)
	v_add_u32_e32 v17, v17, v4
	s_waitcnt vmcnt(9)
	v_add_u32_e32 v17, v17, v5
	s_waitcnt vmcnt(8)
	v_add_u32_e32 v17, v17, v6
	s_waitcnt vmcnt(7)
	v_add_u32_e32 v17, v17, v7
	s_waitcnt vmcnt(6)
	v_add_u32_e32 v17, v17, v8
	s_waitcnt vmcnt(5)
	v_add_u32_e32 v17, v17, v9
	s_waitcnt vmcnt(4)
	v_add_u32_e32 v17, v17, v10
	s_waitcnt vmcnt(3)
	v_add_u32_e32 v17, v17, v11
	s_waitcnt vmcnt(2)
	v_add_u32_e32 v17, v17, v12
	s_waitcnt vmcnt(1)
	v_add_u32_e32 v17, v17, v13
	s_waitcnt vmcnt(0)
	v_add_u32_e32 v17, v17, v14
	v_cmp_eq_u32_e32 vcc, s16, v17
	s_cbranch_vccnz .LBB0_3948
	s_and_b32 s10, s17, 0xff
	s_cmp_eq_u32 s10, 0
	s_mov_b64 s[10:11], -1
	s_mov_b64 s[14:15], -1
	s_nop 0
	s_cbranch_scc1 .LBB0_3953
	s_and_b64 vcc, exec, s[14:15]
	s_cbranch_vccz .LBB0_3948

.LBB0_3965:
	s_and_b32 s16, s20, 0xff
	s_mov_b64 s[14:15], -1
	s_cmp_lg_u32 s16, 0
	s_mov_b64 s[18:19], -1
	s_nop 0
	s_cbranch_scc0 .LBB0_3968
	s_and_b64 vcc, exec, s[18:19]
	s_cbranch_vccz .LBB0_3964

.LBB0_3982:
	s_and_b32 s16, s22, 0xff
	s_cmp_lg_u32 s16, 0
	s_mov_b64 s[18:19], -1
	s_nop 0
	s_cbranch_scc0 .LBB0_3985
	s_mov_b64 s[20:21], -1
	s_and_b64 vcc, exec, s[18:19]
	s_cbranch_vccz .LBB0_3981
